# grid barrier: L1 invalidate issued at arrival (overlapping the wait / the leader's L2 write-back) instead of after the release
# speedup vs baseline: 1.0859x; 1.0141x over previous
.LBB0_96:
	s_lshl_b32 s20, s36, 6
	s_add_i32 s2, s20, 0x500
	s_mov_b32 s3, 0
	s_lshl_b64 s[0:1], s[2:3], 2
	s_add_u32 s0, s34, s0
	s_addc_u32 s1, s35, s1
	v_mov_b32_e32 v1, 1
	v_mov_b64_e32 v[4:5], s[0:1]
	flat_atomic_add v1, v[4:5], v1 sc0
	v_cvt_f32_u32_e32 v3, v2
	v_sub_u32_e32 v4, 0, v2
	v_rcp_iflag_f32_e32 v3, v3
	s_nop 0
	v_mul_f32_e32 v3, 0x4f7ffffe, v3
	v_cvt_u32_f32_e32 v3, v3
	v_mul_lo_u32 v4, v4, v3
	v_mul_hi_u32 v4, v3, v4
	v_add_u32_e32 v3, v3, v4
	s_waitcnt vmcnt(0) lgkmcnt(0)
	v_mul_hi_u32 v3, v1, v3
	v_mul_lo_u32 v5, v3, v2
	v_add_u32_e32 v4, 1, v1
	v_sub_u32_e32 v1, v1, v5
	v_add_u32_e32 v6, 1, v3
	v_cmp_ge_u32_e32 vcc, v1, v2
	v_sub_u32_e32 v5, v1, v2
	s_nop 0
	v_cndmask_b32_e32 v3, v3, v6, vcc
	v_cndmask_b32_e32 v1, v1, v5, vcc
	v_add_u32_e32 v5, 1, v3
	v_cmp_ge_u32_e32 vcc, v1, v2
	s_nop 1
	v_cndmask_b32_e32 v1, v3, v5, vcc
	v_mad_u64_u32 v[2:3], s[0:1], v2, v1, v[2:3]
	v_cmp_ne_u32_e32 vcc, v4, v2
	s_and_saveexec_b64 s[0:1], vcc
	s_xor_b64 s[0:1], exec, s[0:1]
	s_cbranch_execz .LBB0_109
	buffer_inv sc1
	s_movk_i32 s2, 0xd40
	s_lshl_b64 s[2:3], s[2:3], 2
	s_add_u32 s4, s34, s2
	s_addc_u32 s5, s35, s3
	v_mov_b64_e32 v[2:3], s[4:5]
	flat_load_dword v0, v[2:3] sc1
	s_waitcnt vmcnt(0) lgkmcnt(0)
	v_cmp_eq_u32_e32 vcc, v0, v1
	s_and_saveexec_b64 s[2:3], vcc
	s_cbranch_execz .LBB0_108
	s_mov_b32 s21, 1
	s_mov_b64 s[6:7], 0
	s_branch .LBB0_100

.LBB0_108:
	s_or_b64 exec, exec, s[2:3]
	s_waitcnt vmcnt(0) lgkmcnt(0)
	s_waitcnt vmcnt(0)
.LBB0_109:
	s_andn2_saveexec_b64 s[0:1], s[0:1]
	s_cbranch_execz .LBB0_125
	v_mov_b32_e32 v1, s34
	v_add_co_u32_e32 v2, vcc, 0x3000, v1
	v_mov_b32_e32 v1, s35
	buffer_wbl2 sc1
	buffer_inv sc1
	s_waitcnt vmcnt(0)
	v_addc_co_u32_e32 v3, vcc, 0, v1, vcc
	v_mov_b32_e32 v1, 1
	flat_atomic_add v1, v[2:3], v1 offset:1024 sc0
	v_cvt_f32_u32_e32 v2, v0
	v_sub_u32_e32 v3, 0, v0
	s_add_u32 s0, s34, 0x3500
	s_addc_u32 s1, s35, 0
	v_rcp_iflag_f32_e32 v2, v2
	s_mov_b64 s[4:5], -1
	v_mul_f32_e32 v2, 0x4f7ffffe, v2
	v_cvt_u32_f32_e32 v2, v2
	v_mul_lo_u32 v3, v3, v2
	v_mul_hi_u32 v3, v2, v3
	v_add_u32_e32 v2, v2, v3
	s_waitcnt vmcnt(0) lgkmcnt(0)
	v_mul_hi_u32 v2, v1, v2
	v_mul_lo_u32 v4, v2, v0
	v_add_u32_e32 v3, 1, v1
	v_sub_u32_e32 v1, v1, v4
	v_add_u32_e32 v5, 1, v2
	v_cmp_ge_u32_e32 vcc, v1, v0
	v_sub_u32_e32 v4, v1, v0
	s_nop 0
	v_cndmask_b32_e32 v2, v2, v5, vcc
	v_cndmask_b32_e32 v1, v1, v4, vcc
	v_add_u32_e32 v4, 1, v2
	v_cmp_ge_u32_e32 vcc, v1, v0
	s_nop 1
	v_cndmask_b32_e32 v2, v2, v4, vcc
	v_mad_u64_u32 v[0:1], s[2:3], v0, v2, v[0:1]
	v_cmp_ne_u32_e32 vcc, v3, v0
	v_mov_b64_e32 v[0:1], s[0:1]
	s_and_saveexec_b64 s[2:3], vcc
	s_cbranch_execz .LBB0_122
	v_mov_b64_e32 v[0:1], s[0:1]
	flat_load_dword v0, v[0:1] sc1
	s_mov_b64 s[8:9], 0
	s_waitcnt vmcnt(0) lgkmcnt(0)
	v_cmp_eq_u32_e32 vcc, v0, v2
	s_and_saveexec_b64 s[6:7], vcc
	s_cbranch_execz .LBB0_121
	s_add_u32 s4, s34, 0x200
	s_addc_u32 s5, s35, 0
	s_mov_b32 s21, 1
	s_branch .LBB0_114

.LBB0_124:
	s_or_b64 exec, exec, s[0:1]
	s_add_i32 s0, s20, 0x900
	s_mov_b32 s1, 0
	s_lshl_b64 s[0:1], s[0:1], 2
	s_add_u32 s0, s34, s0
	s_addc_u32 s1, s35, s1
	v_mov_b32_e32 v2, 1
	v_mov_b64_e32 v[0:1], s[0:1]
	s_waitcnt vmcnt(0) lgkmcnt(0)
	flat_atomic_add v[0:1], v2
	s_waitcnt vmcnt(0)

.LBB0_126:
	s_or_b64 exec, exec, s[0:1]
	s_add_i32 s82, s20, 0x900
	s_lshl_b64 s[0:1], s[82:83], 2
	s_add_u32 s0, s34, s0
	s_addc_u32 s1, s35, s1
	v_mov_b64_e32 v[0:1], s[0:1]
	s_waitcnt vmcnt(0) lgkmcnt(0)
	flat_atomic_add v[0:1], v209
	s_waitcnt vmcnt(0)

.LBB0_188:
	s_lshl_b32 s20, s36, 6
	s_add_i32 s82, s20, 0x500
	s_lshl_b64 s[0:1], s[82:83], 2
	s_add_u32 s0, s34, s0
	s_addc_u32 s1, s35, s1
	v_mov_b64_e32 v[4:5], s[0:1]
	flat_atomic_add v1, v[4:5], v209 sc0
	v_cvt_f32_u32_e32 v3, v2
	v_sub_u32_e32 v4, 0, v2
	v_rcp_iflag_f32_e32 v3, v3
	s_nop 0
	v_mul_f32_e32 v3, 0x4f7ffffe, v3
	v_cvt_u32_f32_e32 v3, v3
	v_mul_lo_u32 v4, v4, v3
	v_mul_hi_u32 v4, v3, v4
	v_add_u32_e32 v3, v3, v4
	s_waitcnt vmcnt(0) lgkmcnt(0)
	v_mul_hi_u32 v3, v1, v3
	v_mul_lo_u32 v5, v3, v2
	v_add_u32_e32 v4, 1, v1
	v_sub_u32_e32 v1, v1, v5
	v_add_u32_e32 v6, 1, v3
	v_cmp_ge_u32_e32 vcc, v1, v2
	v_sub_u32_e32 v5, v1, v2
	s_nop 0
	v_cndmask_b32_e32 v3, v3, v6, vcc
	v_cndmask_b32_e32 v1, v1, v5, vcc
	v_add_u32_e32 v5, 1, v3
	v_cmp_ge_u32_e32 vcc, v1, v2
	s_nop 1
	v_cndmask_b32_e32 v1, v3, v5, vcc
	v_mad_u64_u32 v[2:3], s[0:1], v2, v1, v[2:3]
	v_cmp_ne_u32_e32 vcc, v4, v2
	s_and_saveexec_b64 s[0:1], vcc
	s_xor_b64 s[0:1], exec, s[0:1]
	s_cbranch_execz .LBB0_201
	buffer_inv sc1
	s_movk_i32 s82, 0xd40
	s_lshl_b64 s[2:3], s[82:83], 2
	s_add_u32 s4, s34, s2
	s_addc_u32 s5, s35, s3
	v_mov_b64_e32 v[2:3], s[4:5]
	flat_load_dword v0, v[2:3] sc1
	s_waitcnt vmcnt(0) lgkmcnt(0)
	v_cmp_eq_u32_e32 vcc, v0, v1
	s_and_saveexec_b64 s[2:3], vcc
	s_cbranch_execz .LBB0_200
	s_mov_b32 s21, 1
	s_mov_b64 s[6:7], 0
	s_branch .LBB0_192

.LBB0_201:
	s_andn2_saveexec_b64 s[0:1], s[0:1]
	s_cbranch_execz .LBB0_217
	v_mov_b32_e32 v1, s34
	v_add_co_u32_e32 v2, vcc, 0x3000, v1
	v_mov_b32_e32 v1, s35
	buffer_wbl2 sc1
	buffer_inv sc1
	s_waitcnt vmcnt(0)
	v_addc_co_u32_e32 v3, vcc, 0, v1, vcc
	flat_atomic_add v1, v[2:3], v209 offset:1024 sc0
	v_cvt_f32_u32_e32 v2, v0
	v_sub_u32_e32 v3, 0, v0
	s_add_u32 s0, s34, 0x3500
	s_addc_u32 s1, s35, 0
	v_rcp_iflag_f32_e32 v2, v2
	s_mov_b64 s[4:5], -1
	v_mul_f32_e32 v2, 0x4f7ffffe, v2
	v_cvt_u32_f32_e32 v2, v2
	v_mul_lo_u32 v3, v3, v2
	v_mul_hi_u32 v3, v2, v3
	v_add_u32_e32 v2, v2, v3
	s_waitcnt vmcnt(0) lgkmcnt(0)
	v_mul_hi_u32 v2, v1, v2
	v_mul_lo_u32 v4, v2, v0
	v_add_u32_e32 v3, 1, v1
	v_sub_u32_e32 v1, v1, v4
	v_add_u32_e32 v5, 1, v2
	v_cmp_ge_u32_e32 vcc, v1, v0
	v_sub_u32_e32 v4, v1, v0
	s_nop 0
	v_cndmask_b32_e32 v2, v2, v5, vcc
	v_cndmask_b32_e32 v1, v1, v4, vcc
	v_add_u32_e32 v4, 1, v2
	v_cmp_ge_u32_e32 vcc, v1, v0
	s_nop 1
	v_cndmask_b32_e32 v2, v2, v4, vcc
	v_mad_u64_u32 v[0:1], s[2:3], v0, v2, v[0:1]
	v_cmp_ne_u32_e32 vcc, v3, v0
	v_mov_b64_e32 v[0:1], s[0:1]
	s_and_saveexec_b64 s[2:3], vcc
	s_cbranch_execz .LBB0_214
	v_mov_b64_e32 v[0:1], s[0:1]
	flat_load_dword v0, v[0:1] sc1
	s_mov_b64 s[8:9], 0
	s_waitcnt vmcnt(0) lgkmcnt(0)
	v_cmp_eq_u32_e32 vcc, v0, v2
	s_and_saveexec_b64 s[6:7], vcc
	s_cbranch_execz .LBB0_213
	s_add_u32 s4, s34, 0x200
	s_addc_u32 s5, s35, 0
	s_mov_b32 s21, 1
	s_branch .LBB0_206

.LBB0_286:
	s_lshl_b32 s20, s36, 6
	s_add_i32 s0, s20, 0x500
	s_mov_b32 s1, s83
	s_lshl_b64 s[0:1], s[0:1], 2
	s_add_u32 s0, s34, s0
	s_addc_u32 s1, s35, s1
	v_mov_b64_e32 v[4:5], s[0:1]
	flat_atomic_add v3, v[4:5], v209 sc0
	v_cvt_f32_u32_e32 v1, v2
	v_sub_u32_e32 v4, 0, v2
	v_rcp_iflag_f32_e32 v1, v1
	s_nop 0
	v_mul_f32_e32 v1, 0x4f7ffffe, v1
	v_cvt_u32_f32_e32 v1, v1
	v_mul_lo_u32 v4, v4, v1
	v_mul_hi_u32 v4, v1, v4
	v_add_u32_e32 v1, v1, v4
	s_waitcnt vmcnt(0) lgkmcnt(0)
	v_mul_hi_u32 v1, v3, v1
	v_mul_lo_u32 v4, v1, v2
	v_sub_u32_e32 v4, v3, v4
	v_cmp_ge_u32_e32 vcc, v4, v2
	v_add_u32_e32 v5, 1, v1
	s_nop 0
	v_cndmask_b32_e32 v1, v1, v5, vcc
	v_sub_u32_e32 v5, v4, v2
	v_cndmask_b32_e32 v4, v4, v5, vcc
	v_cmp_ge_u32_e32 vcc, v4, v2
	v_add_u32_e32 v4, 1, v1
	s_nop 0
	v_cndmask_b32_e32 v1, v1, v4, vcc
	v_add_u32_e32 v4, 1, v3
	v_mad_u64_u32 v[2:3], s[0:1], v2, v1, v[2:3]
	v_cmp_ne_u32_e32 vcc, v4, v2
	s_and_saveexec_b64 s[0:1], vcc
	s_xor_b64 s[0:1], exec, s[0:1]
	s_cbranch_execz .LBB0_299
	buffer_inv sc1
	s_movk_i32 s2, 0xd40
	s_mov_b32 s3, s83
	s_lshl_b64 s[2:3], s[2:3], 2
	s_add_u32 s4, s34, s2
	s_addc_u32 s5, s35, s3
	v_mov_b64_e32 v[2:3], s[4:5]
	flat_load_dword v0, v[2:3] sc1
	s_waitcnt vmcnt(0) lgkmcnt(0)
	v_cmp_eq_u32_e32 vcc, v0, v1
	s_and_saveexec_b64 s[2:3], vcc
	s_cbranch_execz .LBB0_298
	s_mov_b32 s21, 1
	s_mov_b64 s[6:7], 0
	s_branch .LBB0_290

.LBB0_299:
	s_andn2_saveexec_b64 s[0:1], s[0:1]
	s_cbranch_execz .LBB0_315
	v_mov_b32_e32 v1, s34
	v_add_co_u32_e32 v2, vcc, 0x3000, v1
	v_mov_b32_e32 v1, s35
	buffer_wbl2 sc1
	buffer_inv sc1
	s_waitcnt vmcnt(0)
	v_addc_co_u32_e32 v3, vcc, 0, v1, vcc
	flat_atomic_add v1, v[2:3], v209 offset:1024 sc0
	v_cvt_f32_u32_e32 v2, v0
	v_sub_u32_e32 v3, 0, v0
	s_mov_b64 s[4:5], -1
	v_rcp_iflag_f32_e32 v2, v2
	s_nop 0
	v_mul_f32_e32 v2, 0x4f7ffffe, v2
	v_cvt_u32_f32_e32 v2, v2
	v_mul_lo_u32 v3, v3, v2
	v_mul_hi_u32 v3, v2, v3
	v_add_u32_e32 v2, v2, v3
	s_waitcnt vmcnt(0) lgkmcnt(0)
	v_mul_hi_u32 v2, v1, v2
	v_mul_lo_u32 v3, v2, v0
	v_sub_u32_e32 v3, v1, v3
	v_cmp_ge_u32_e32 vcc, v3, v0
	v_add_u32_e32 v4, 1, v2
	s_nop 0
	v_cndmask_b32_e32 v2, v2, v4, vcc
	v_sub_u32_e32 v4, v3, v0
	v_cndmask_b32_e32 v3, v3, v4, vcc
	v_cmp_ge_u32_e32 vcc, v3, v0
	v_add_u32_e32 v3, 1, v2
	s_nop 0
	v_cndmask_b32_e32 v2, v2, v3, vcc
	v_add_u32_e32 v3, 1, v1
	v_mad_u64_u32 v[0:1], s[0:1], v0, v2, v[0:1]
	s_add_u32 s0, s34, 0x3500
	s_addc_u32 s1, s35, 0
	v_cmp_ne_u32_e32 vcc, v3, v0
	v_mov_b64_e32 v[0:1], s[0:1]
	s_and_saveexec_b64 s[2:3], vcc
	s_cbranch_execz .LBB0_312
	v_mov_b64_e32 v[0:1], s[0:1]
	flat_load_dword v0, v[0:1] sc1
	s_mov_b64 s[8:9], 0
	s_waitcnt vmcnt(0) lgkmcnt(0)
	v_cmp_eq_u32_e32 vcc, v0, v2
	s_and_saveexec_b64 s[6:7], vcc
	s_cbranch_execz .LBB0_311
	s_add_u32 s4, s34, 0x200
	s_addc_u32 s5, s35, 0
	s_mov_b32 s21, 1
	s_branch .LBB0_304

.LBB0_314:
	s_or_b64 exec, exec, s[0:1]
	s_add_i32 s0, s20, 0x900
	s_mov_b32 s1, s83
	s_lshl_b64 s[0:1], s[0:1], 2
	s_add_u32 s0, s34, s0
	s_addc_u32 s1, s35, s1
	v_mov_b64_e32 v[0:1], s[0:1]
	s_waitcnt vmcnt(0) lgkmcnt(0)
	flat_atomic_add v[0:1], v209
	s_waitcnt vmcnt(0)

.LBB0_355:
	s_lshl_b32 s22, s38, 6
	s_add_i32 s82, s22, 0x500
	s_lshl_b64 s[0:1], s[82:83], 2
	s_add_u32 s0, s36, s0
	s_addc_u32 s1, s37, s1
	v_mov_b64_e32 v[4:5], s[0:1]
	flat_atomic_add v3, v[4:5], v209 sc0
	v_cvt_f32_u32_e32 v1, v2
	v_sub_u32_e32 v4, 0, v2
	v_rcp_iflag_f32_e32 v1, v1
	s_nop 0
	v_mul_f32_e32 v1, 0x4f7ffffe, v1
	v_cvt_u32_f32_e32 v1, v1
	v_mul_lo_u32 v4, v4, v1
	v_mul_hi_u32 v4, v1, v4
	v_add_u32_e32 v1, v1, v4
	s_waitcnt vmcnt(0) lgkmcnt(0)
	v_mul_hi_u32 v1, v3, v1
	v_mul_lo_u32 v4, v1, v2
	v_sub_u32_e32 v4, v3, v4
	v_cmp_ge_u32_e32 vcc, v4, v2
	v_add_u32_e32 v5, 1, v1
	s_nop 0
	v_cndmask_b32_e32 v1, v1, v5, vcc
	v_sub_u32_e32 v5, v4, v2
	v_cndmask_b32_e32 v4, v4, v5, vcc
	v_cmp_ge_u32_e32 vcc, v4, v2
	v_add_u32_e32 v4, 1, v1
	s_nop 0
	v_cndmask_b32_e32 v1, v1, v4, vcc
	v_add_u32_e32 v4, 1, v3
	v_mad_u64_u32 v[2:3], s[0:1], v2, v1, v[2:3]
	v_cmp_ne_u32_e32 vcc, v4, v2
	s_and_saveexec_b64 s[0:1], vcc
	s_xor_b64 s[0:1], exec, s[0:1]
	s_cbranch_execz .LBB0_368
	buffer_inv sc1
	s_movk_i32 s82, 0xd40
	s_lshl_b64 s[2:3], s[82:83], 2
	s_add_u32 s6, s36, s2
	s_addc_u32 s7, s37, s3
	v_mov_b64_e32 v[2:3], s[6:7]
	flat_load_dword v0, v[2:3] sc1
	s_waitcnt vmcnt(0) lgkmcnt(0)
	v_cmp_eq_u32_e32 vcc, v0, v1
	s_and_saveexec_b64 s[2:3], vcc
	s_cbranch_execz .LBB0_367
	s_mov_b32 s23, 1
	s_mov_b64 s[8:9], 0
	s_branch .LBB0_359

.LBB0_368:
	s_andn2_saveexec_b64 s[0:1], s[0:1]
	s_cbranch_execz .LBB0_384
	v_mov_b32_e32 v1, s36
	v_add_co_u32_e32 v2, vcc, 0x3000, v1
	v_mov_b32_e32 v1, s37
	buffer_wbl2 sc1
	buffer_inv sc1
	s_waitcnt vmcnt(0)
	v_addc_co_u32_e32 v3, vcc, 0, v1, vcc
	flat_atomic_add v1, v[2:3], v209 offset:1024 sc0
	v_cvt_f32_u32_e32 v2, v0
	v_sub_u32_e32 v3, 0, v0
	s_mov_b64 s[6:7], -1
	v_rcp_iflag_f32_e32 v2, v2
	s_nop 0
	v_mul_f32_e32 v2, 0x4f7ffffe, v2
	v_cvt_u32_f32_e32 v2, v2
	v_mul_lo_u32 v3, v3, v2
	v_mul_hi_u32 v3, v2, v3
	v_add_u32_e32 v2, v2, v3
	s_waitcnt vmcnt(0) lgkmcnt(0)
	v_mul_hi_u32 v2, v1, v2
	v_mul_lo_u32 v3, v2, v0
	v_sub_u32_e32 v3, v1, v3
	v_cmp_ge_u32_e32 vcc, v3, v0
	v_add_u32_e32 v4, 1, v2
	s_nop 0
	v_cndmask_b32_e32 v2, v2, v4, vcc
	v_sub_u32_e32 v4, v3, v0
	v_cndmask_b32_e32 v3, v3, v4, vcc
	v_cmp_ge_u32_e32 vcc, v3, v0
	v_add_u32_e32 v3, 1, v2
	s_nop 0
	v_cndmask_b32_e32 v2, v2, v3, vcc
	v_add_u32_e32 v3, 1, v1
	v_mad_u64_u32 v[0:1], s[0:1], v0, v2, v[0:1]
	s_add_u32 s0, s36, 0x3500
	s_addc_u32 s1, s37, 0
	v_cmp_ne_u32_e32 vcc, v3, v0
	v_mov_b64_e32 v[0:1], s[0:1]
	s_and_saveexec_b64 s[2:3], vcc
	s_cbranch_execz .LBB0_381
	v_mov_b64_e32 v[0:1], s[0:1]
	flat_load_dword v0, v[0:1] sc1
	s_mov_b64 s[10:11], 0
	s_waitcnt vmcnt(0) lgkmcnt(0)
	v_cmp_eq_u32_e32 vcc, v0, v2
	s_and_saveexec_b64 s[8:9], vcc
	s_cbranch_execz .LBB0_380
	s_add_u32 s6, s36, 0x200
	s_addc_u32 s7, s37, 0
	s_mov_b32 s23, 1
	s_branch .LBB0_373

.LBB0_383:
	s_or_b64 exec, exec, s[0:1]
	s_add_i32 s82, s22, 0x900
	s_lshl_b64 s[0:1], s[82:83], 2
	s_add_u32 s0, s36, s0
	s_addc_u32 s1, s37, s1
	v_mov_b64_e32 v[0:1], s[0:1]
	s_waitcnt vmcnt(0) lgkmcnt(0)
	flat_atomic_add v[0:1], v209
	s_waitcnt vmcnt(0)

.LBB0_440:
	s_lshl_b32 s20, s36, 6
	s_add_i32 s82, s20, 0x500
	s_lshl_b64 s[0:1], s[82:83], 2
	s_add_u32 s0, s34, s0
	s_addc_u32 s1, s35, s1
	v_mov_b64_e32 v[4:5], s[0:1]
	flat_atomic_add v3, v[4:5], v209 sc0
	v_cvt_f32_u32_e32 v1, v2
	v_sub_u32_e32 v4, 0, v2
	v_rcp_iflag_f32_e32 v1, v1
	s_nop 0
	v_mul_f32_e32 v1, 0x4f7ffffe, v1
	v_cvt_u32_f32_e32 v1, v1
	v_mul_lo_u32 v4, v4, v1
	v_mul_hi_u32 v4, v1, v4
	v_add_u32_e32 v1, v1, v4
	s_waitcnt vmcnt(0) lgkmcnt(0)
	v_mul_hi_u32 v1, v3, v1
	v_mul_lo_u32 v4, v1, v2
	v_sub_u32_e32 v4, v3, v4
	v_cmp_ge_u32_e32 vcc, v4, v2
	v_add_u32_e32 v5, 1, v1
	s_nop 0
	v_cndmask_b32_e32 v1, v1, v5, vcc
	v_sub_u32_e32 v5, v4, v2
	v_cndmask_b32_e32 v4, v4, v5, vcc
	v_cmp_ge_u32_e32 vcc, v4, v2
	v_add_u32_e32 v4, 1, v1
	s_nop 0
	v_cndmask_b32_e32 v1, v1, v4, vcc
	v_add_u32_e32 v4, 1, v3
	v_mad_u64_u32 v[2:3], s[0:1], v2, v1, v[2:3]
	v_cmp_ne_u32_e32 vcc, v4, v2
	s_and_saveexec_b64 s[0:1], vcc
	s_xor_b64 s[0:1], exec, s[0:1]
	s_cbranch_execz .LBB0_453
	buffer_inv sc1
	s_movk_i32 s82, 0xd40
	s_lshl_b64 s[2:3], s[82:83], 2
	s_add_u32 s4, s34, s2
	s_addc_u32 s5, s35, s3
	v_mov_b64_e32 v[2:3], s[4:5]
	flat_load_dword v0, v[2:3] sc1
	s_waitcnt vmcnt(0) lgkmcnt(0)
	v_cmp_eq_u32_e32 vcc, v0, v1
	s_and_saveexec_b64 s[2:3], vcc
	s_cbranch_execz .LBB0_452
	s_mov_b32 s21, 1
	s_mov_b64 s[6:7], 0
	s_branch .LBB0_444

.LBB0_1069:
	v_mov_b32_e32 v1, s34
	v_add_co_u32_e32 v2, vcc, 0x3000, v1
	v_mov_b32_e32 v1, s35
	buffer_wbl2 sc1
	buffer_inv sc1
	s_waitcnt vmcnt(0)
	v_addc_co_u32_e32 v3, vcc, 0, v1, vcc
	flat_atomic_add v1, v[2:3], v209 offset:1024 sc0
	v_cvt_f32_u32_e32 v2, v0
	v_sub_u32_e32 v3, 0, v0
	s_mov_b64 s[4:5], -1
	v_rcp_iflag_f32_e32 v2, v2
	s_nop 0
	v_mul_f32_e32 v2, 0x4f7ffffe, v2
	v_cvt_u32_f32_e32 v2, v2
	v_mul_lo_u32 v3, v3, v2
	v_mul_hi_u32 v3, v2, v3
	v_add_u32_e32 v2, v2, v3
	s_waitcnt vmcnt(0) lgkmcnt(0)
	v_mul_hi_u32 v2, v1, v2
	v_mul_lo_u32 v3, v2, v0
	v_sub_u32_e32 v3, v1, v3
	v_cmp_ge_u32_e32 vcc, v3, v0
	v_add_u32_e32 v4, 1, v2
	s_nop 0
	v_cndmask_b32_e32 v2, v2, v4, vcc
	v_sub_u32_e32 v4, v3, v0
	v_cndmask_b32_e32 v3, v3, v4, vcc
	v_cmp_ge_u32_e32 vcc, v3, v0
	v_add_u32_e32 v3, 1, v2
	s_nop 0
	v_cndmask_b32_e32 v2, v2, v3, vcc
	v_add_u32_e32 v3, 1, v1
	v_mad_u64_u32 v[0:1], s[0:1], v0, v2, v[0:1]
	s_add_u32 s0, s34, 0x3500
	s_addc_u32 s1, s35, 0
	v_cmp_ne_u32_e32 vcc, v3, v0
	v_mov_b64_e32 v[0:1], s[0:1]
	s_and_saveexec_b64 s[2:3], vcc
	s_cbranch_execz .LBB0_1081
	v_mov_b64_e32 v[0:1], s[0:1]
	flat_load_dword v0, v[0:1] sc1
	s_mov_b64 s[8:9], 0
	s_waitcnt vmcnt(0) lgkmcnt(0)
	v_cmp_eq_u32_e32 vcc, v0, v2
	s_and_saveexec_b64 s[6:7], vcc
	s_cbranch_execz .LBB0_1080
	s_add_u32 s4, s34, 0x200
	s_addc_u32 s5, s35, 0
	s_mov_b32 s21, 1
	s_branch .LBB0_1073
